# baseline (speedup 1.0000x reference)
; template <int MODE> ...
;     ...
;           float lsum = 0.f;
; #pragma unroll
;           for (int i = 0; i < 16; ++i) {
;             const float pv = __builtin_amdgcn_exp2f(S[i] - m_run);
;             S[i] = pv;
;             lsum += pv;
;           }
;           l_run += lsum;
;         } else {
;           float gs[4], gp[4], suf[4];
; #pragma unroll
;           for (int m = 0; m < 4; ++m) {
;             float acc4 = 0.f;
; #pragma unroll
;             for (int e2 = 0; e2 < 4; ++e2) {
;               const int key = kbase + 8 * m + e2;
;               const float lg = S[4 * m + e2];
;               const float sp = fmaxf(lg, 0.f) + __logf(1.f + __expf(-fabsf(lg)));
;               acc4 += (key < t_q) ? -sp : 0.f;
;             }
;             gs[m] = acc4;
;           }
; #pragma unroll
;           for (int m = 0; m < 4; ++m) gp[m] = __shfl_xor(gs[m], 32);
;           float run = 0.f;
; #pragma unroll
;           for (int m = 3; m >= 0; --m) {
;             suf[m] = run + ((g == 0) ? gp[m] : 0.f);
;             run += gs[m] + gp[m];
;           }
; #pragma unroll
;           for (int m = 0; m < 4; ++m) {
;             float later = carry + suf[m];
; #pragma unroll
;     ...
;               const int key = kbase + 8 * m + e2;
;               const bool ok = key < t_q;
;               const float lg = S[4 * m + e2];
;               const float sp = fmaxf(lg, 0.f) + __logf(1.f + __expf(-fabsf(lg)));
;               S[4 * m + e2] = ok ? __expf((lg - sp) + later) : 0.f;
;               later += ok ? -sp : 0.f;
;             }
;           }
;           carry += run;
;         }
;         const char* vbase = Vs + vcur * VSZ + ql * 136 + g * 8 + sub * 64;
; #pragma unroll
;         for (int hh = 0; hh < 2; ++hh) {
;           union { bf16x8 v; unsigned u[4]; } pf;
; #pragma unroll
;           for (int j = 0; j < 4; ++j) pf.u[j] = pk2(S[8 * hh + 2 * j], S[8 * hh + 2 * j + 1]);
; #pragma unroll
;           for (int mb = 0; mb < 4; ++mb) {
;             const char* vp = vbase + mb * 32 * 136 + hh * 32;
;             const uint2 lo = *reinterpret_cast<const uint2*>(vp);
;             const uint2 hi = *reinterpret_cast<const uint2*>(vp + 16);
;             union { bf16x8 v; unsigned u[4]; } vf;
;             vf.u[0] = lo.x; vf.u[1] = lo.y; vf.u[2] = hi.x; vf.u[3] = hi.y;
;             O[mb] = __builtin_amdgcn_mfma_f32_32x32x16_bf16(vf.v, pf.v, O[mb], 0, 0, 0);
;           }
.LBB0_348:
	v_sub_f32_e32 v0, v2, v217
	v_exp_f32_e32 v2, v0
	v_sub_f32_e32 v0, v3, v217
	v_exp_f32_e32 v3, v0
	v_sub_f32_e32 v0, v4, v217
	v_exp_f32_e32 v4, v0
	v_sub_f32_e32 v0, v5, v217
	v_exp_f32_e32 v5, v0
	v_sub_f32_e32 v0, v6, v217
	v_exp_f32_e32 v6, v0
	v_sub_f32_e32 v0, v7, v217
	v_exp_f32_e32 v7, v0
	v_sub_f32_e32 v8, v8, v217
	v_sub_f32_e32 v9, v9, v217
	v_exp_f32_e32 v8, v8
	v_exp_f32_e32 v9, v9
	v_cvt_pk_bf16_f32 v194, v2, v3
	v_cvt_pk_bf16_f32 v195, v4, v5
	v_cvt_pk_bf16_f32 v196, v6, v7
	v_cvt_pk_bf16_f32 v197, v8, v9
	s_waitcnt lgkmcnt(7)
	v_mfma_f32_32x32x16_bf16 v[80:95], v[218:221], v[194:197], v[80:95]
	v_sub_f32_e32 v10, v10, v217
	v_sub_f32_e32 v11, v11, v217
	v_sub_f32_e32 v12, v12, v217
	v_sub_f32_e32 v13, v13, v217
	s_waitcnt lgkmcnt(6)
	v_mfma_f32_32x32x16_bf16 v[64:79], v[222:225], v[194:197], v[64:79]
	v_sub_f32_e32 v14, v14, v217
	v_sub_f32_e32 v15, v15, v217
	v_sub_f32_e32 v16, v16, v217
	v_sub_f32_e32 v17, v17, v217
	v_exp_f32_e32 v10, v10
	v_exp_f32_e32 v11, v11
	s_waitcnt lgkmcnt(5)
	v_mfma_f32_32x32x16_bf16 v[48:63], v[226:229], v[194:197], v[48:63]
	v_exp_f32_e32 v12, v12
	v_exp_f32_e32 v13, v13
	v_exp_f32_e32 v14, v14
	v_exp_f32_e32 v15, v15
	v_exp_f32_e32 v16, v16
	v_exp_f32_e32 v17, v17
	s_waitcnt lgkmcnt(4)
	v_mfma_f32_32x32x16_bf16 v[32:47], v[230:233], v[194:197], v[32:47]
	v_cvt_pk_bf16_f32 v190, v10, v11
	v_cvt_pk_bf16_f32 v191, v12, v13
	v_cvt_pk_bf16_f32 v192, v14, v15
	v_cvt_pk_bf16_f32 v193, v16, v17
	v_add_f32_e32 v180, 0, v2
	v_add_f32_e32 v180, v3, v180
	s_waitcnt lgkmcnt(3)
	v_mfma_f32_32x32x16_bf16 v[80:95], v[234:237], v[190:193], v[80:95]
	v_add_f32_e32 v180, v4, v180
	v_add_f32_e32 v180, v5, v180
	v_add_f32_e32 v180, v6, v180
	v_add_f32_e32 v180, v7, v180
	v_add_f32_e32 v180, v8, v180
	v_add_f32_e32 v180, v9, v180
	s_waitcnt lgkmcnt(2)
	v_mfma_f32_32x32x16_bf16 v[64:79], v[238:241], v[190:193], v[64:79]
	v_add_f32_e32 v180, v10, v180
	v_add_f32_e32 v0, v11, v180
	v_add_f32_e32 v0, v12, v0
	v_add_f32_e32 v0, v13, v0
	v_add_f32_e32 v0, v14, v0
	v_add_f32_e32 v0, v15, v0
	s_waitcnt lgkmcnt(1)
	v_mfma_f32_32x32x16_bf16 v[48:63], v[242:245], v[190:193], v[48:63]
	v_add_f32_e32 v0, v16, v0
	v_add_f32_e32 v0, v17, v0
	v_add_f32_e32 v216, v216, v0
	s_waitcnt lgkmcnt(0)
	v_mfma_f32_32x32x16_bf16 v[32:47], v[246:249], v[190:193], v[32:47]

; template <int MODE> ...
;     ...
;         const int kbase = k32 + 4 * g;
;         if (MODE == 0) {
;           const bool diag = (k32 + 31) > w_first;
;           float mx = -1e30f;
;           if (diag) {
; #pragma unroll
;             for (int i = 0; i < 16; ++i) {
;               const int key = kbase + 8 * (i >> 2) + (i & 3);
;               const float sv = (key <= t_q) ? S[i] : -1e30f;
;               S[i] = sv;
;               mx = fmaxf(mx, sv);
;             }
;           } else {
; #pragma unroll
;             for (int i = 0; i < 16; ++i) mx = fmaxf(mx, S[i]);
;           }
;           mx = fmaxf(mx, __shfl_xor(mx, 32));
;     ...
;         const char* vbase = Vs + vcur * VSZ + ql * 136 + g * 8 + sub * 64;
; #pragma unroll
;         for (int hh = 0; hh < 2; ++hh) {
;           union { bf16x8 v; unsigned u[4]; } pf;
; #pragma unroll
;           for (int j = 0; j < 4; ++j) pf.u[j] = pk2(S[8 * hh + 2 * j], S[8 * hh + 2 * j + 1]);
; #pragma unroll
;           for (int mb = 0; mb < 4; ++mb) {
;             const char* vp = vbase + mb * 32 * 136 + hh * 32;
;             const uint2 lo = *reinterpret_cast<const uint2*>(vp);
;             const uint2 hi = *reinterpret_cast<const uint2*>(vp + 16);
.LBB0_352:
	s_or_b64 exec, exec, s[8:9]
	s_mul_i32 s16, s15, 0x4800
	s_and_saveexec_b64 s[8:9], s[10:11]
	s_cbranch_execz .LBB0_360
	v_add_u32_e32 v187, s16, v168
	ds_read_b128 v[218:221], v187 offset:25024
	ds_read_b128 v[222:225], v187 offset:29632
	ds_read_b128 v[226:229], v187 offset:34240
	ds_read_b128 v[230:233], v187 offset:38848
	ds_read_b128 v[234:237], v187 offset:25056
	ds_read_b128 v[238:241], v187 offset:29664
	ds_read_b128 v[242:245], v187 offset:34272
	ds_read_b128 v[246:249], v187 offset:38880
	v_cmp_le_u32_e32 vcc, s14, v166
	s_and_saveexec_b64 s[10:11], vcc
	s_xor_b64 s[10:11], exec, s[10:11]
	s_mov_b32 s17, 0xf149f2ca
	s_nop 3
	v_max3_f32 v0, v2, s17, v3
	v_max3_f32 v0, v0, v4, v5
	v_max3_f32 v0, v0, v6, v7
	v_max3_f32 v0, v0, v8, v9
	v_max3_f32 v0, v0, v10, v11
	v_max3_f32 v0, v0, v12, v13
	v_max3_f32 v0, v0, v14, v15
	v_max3_f32 v0, v0, v16, v17
	s_andn2_saveexec_b64 s[10:11], s[10:11]
	s_cbranch_execz .LBB0_357
	v_add_u32_e32 v0, s14, v165
	v_subrev_u32_e32 v180, 31, v0
	v_cmp_le_i32_e32 vcc, v180, v30
	v_subrev_u32_e32 v181, 29, v0
	s_mov_b32 s17, 0xf149f2ca
	v_cndmask_b32_e32 v2, v202, v2, vcc
	v_cmp_lt_i32_e32 vcc, v180, v30
	s_nop 1
	v_cndmask_b32_e32 v3, v202, v3, vcc
	v_cmp_le_i32_e32 vcc, v181, v30
	v_subrev_u32_e32 v181, 28, v0
	v_max3_f32 v180, v2, s17, v3
	v_cndmask_b32_e32 v4, v202, v4, vcc
	v_cmp_le_i32_e32 vcc, v181, v30
	v_subrev_u32_e32 v181, 23, v0
	s_nop 0
	v_cndmask_b32_e32 v5, v202, v5, vcc
	v_cmp_le_i32_e32 vcc, v181, v30
	v_subrev_u32_e32 v181, 22, v0
	v_max3_f32 v180, v180, v4, v5
	v_cndmask_b32_e32 v6, v202, v6, vcc
	v_cmp_le_i32_e32 vcc, v181, v30
	v_subrev_u32_e32 v181, 21, v0
	s_nop 0
	v_cndmask_b32_e32 v7, v202, v7, vcc
	v_cmp_le_i32_e32 vcc, v181, v30
	v_subrev_u32_e32 v181, 20, v0
	v_max3_f32 v180, v180, v6, v7
	v_cndmask_b32_e32 v8, v202, v8, vcc
	v_cmp_le_i32_e32 vcc, v181, v30
	v_add_u32_e32 v181, -15, v0
	s_nop 0
	v_cndmask_b32_e32 v9, v202, v9, vcc
	v_cmp_le_i32_e32 vcc, v181, v30
	v_add_u32_e32 v181, -14, v0
	v_max3_f32 v180, v180, v8, v9
	v_cndmask_b32_e32 v10, v202, v10, vcc
	v_cmp_le_i32_e32 vcc, v181, v30
	v_add_u32_e32 v181, -13, v0
	s_nop 0
	v_cndmask_b32_e32 v11, v202, v11, vcc
	v_cmp_le_i32_e32 vcc, v181, v30
	v_add_u32_e32 v181, -12, v0
	v_max3_f32 v180, v180, v10, v11
	v_cndmask_b32_e32 v12, v202, v12, vcc
	v_cmp_le_i32_e32 vcc, v181, v30
	v_add_u32_e32 v181, -7, v0
	s_nop 0
	v_cndmask_b32_e32 v13, v202, v13, vcc
	v_cmp_le_i32_e32 vcc, v181, v30
	v_add_u32_e32 v181, -6, v0
	v_max3_f32 v180, v180, v12, v13
	v_cndmask_b32_e32 v14, v202, v14, vcc
	v_cmp_le_i32_e32 vcc, v181, v30
	v_add_u32_e32 v181, -5, v0
	v_add_u32_e32 v0, -4, v0
	v_cndmask_b32_e32 v15, v202, v15, vcc
	v_cmp_le_i32_e32 vcc, v181, v30
	v_max3_f32 v180, v180, v14, v15
	s_nop 0
	v_cndmask_b32_e32 v16, v202, v16, vcc
	v_cmp_le_i32_e32 vcc, v0, v30
	s_nop 1
	v_cndmask_b32_e32 v17, v202, v17, vcc
	v_max3_f32 v0, v180, v16, v17

; template <int MODE> ...
;     ...
;         const int kbase = k32 + 4 * g;
;         if (MODE == 0) {
;           const bool diag = (k32 + 31) > w_first;
;           float mx = -1e30f;
;           if (diag) {
; #pragma unroll
;             for (int i = 0; i < 16; ++i) {
;               const int key = kbase + 8 * (i >> 2) + (i & 3);
;               const float sv = (key <= t_q) ? S[i] : -1e30f;
;               S[i] = sv;
;               mx = fmaxf(mx, sv);
;             }
;           } else {
; #pragma unroll
;             for (int i = 0; i < 16; ++i) mx = fmaxf(mx, S[i]);
;           }
;           mx = fmaxf(mx, __shfl_xor(mx, 32));
;     ...
;         const char* vbase = Vs + vcur * VSZ + ql * 136 + g * 8 + sub * 64;
; #pragma unroll
;         for (int hh = 0; hh < 2; ++hh) {
;           union { bf16x8 v; unsigned u[4]; } pf;
; #pragma unroll
;           for (int j = 0; j < 4; ++j) pf.u[j] = pk2(S[8 * hh + 2 * j], S[8 * hh + 2 * j + 1]);
; #pragma unroll
;           for (int mb = 0; mb < 4; ++mb) {
;             const char* vp = vbase + mb * 32 * 136 + hh * 32;
;             const uint2 lo = *reinterpret_cast<const uint2*>(vp);
;             const uint2 hi = *reinterpret_cast<const uint2*>(vp + 16);
.LBB0_366:
	s_and_saveexec_b64 s[8:9], s[10:11]
	s_cbranch_execz .LBB0_349
	v_add_u32_e32 v187, s16, v168
	ds_read_b128 v[218:221], v187 offset:24960
	ds_read_b128 v[222:225], v187 offset:29568
	ds_read_b128 v[226:229], v187 offset:34176
	ds_read_b128 v[230:233], v187 offset:38784
	ds_read_b128 v[234:237], v187 offset:24992
	ds_read_b128 v[238:241], v187 offset:29600
	ds_read_b128 v[242:245], v187 offset:34208
	ds_read_b128 v[246:249], v187 offset:38816
	s_sub_i32 s10, s14, 32
	v_cmp_le_i32_e32 vcc, s10, v166
	s_and_saveexec_b64 s[10:11], vcc
	s_xor_b64 s[10:11], exec, s[10:11]
	s_mov_b32 s17, 0xf149f2ca
	v_max3_f32 v0, v2, s17, v3
	v_max3_f32 v0, v0, v4, v5
	v_max3_f32 v0, v0, v6, v7
	v_max3_f32 v0, v0, v8, v9
	v_max3_f32 v0, v0, v10, v11
	v_max3_f32 v0, v0, v12, v13
	v_max3_f32 v0, v0, v14, v15
	v_max3_f32 v0, v0, v16, v17
	s_andn2_saveexec_b64 s[10:11], s[10:11]
	s_cbranch_execz .LBB0_371
	v_add_u32_e32 v0, s14, v165
	v_subrev_u32_e32 v180, 63, v0
	v_cmp_le_i32_e32 vcc, v180, v30
	v_subrev_u32_e32 v181, 61, v0
	s_mov_b32 s17, 0xf149f2ca
	v_cndmask_b32_e32 v2, v202, v2, vcc
	v_cmp_lt_i32_e32 vcc, v180, v30
	s_nop 1
	v_cndmask_b32_e32 v3, v202, v3, vcc
	v_cmp_le_i32_e32 vcc, v181, v30
	v_subrev_u32_e32 v181, 60, v0
	v_max3_f32 v180, v2, s17, v3
	v_cndmask_b32_e32 v4, v202, v4, vcc
	v_cmp_le_i32_e32 vcc, v181, v30
	v_subrev_u32_e32 v181, 55, v0
	s_nop 0
	v_cndmask_b32_e32 v5, v202, v5, vcc
	v_cmp_le_i32_e32 vcc, v181, v30
	v_subrev_u32_e32 v181, 54, v0
	v_max3_f32 v180, v180, v4, v5
	v_cndmask_b32_e32 v6, v202, v6, vcc
	v_cmp_le_i32_e32 vcc, v181, v30
	v_subrev_u32_e32 v181, 53, v0
	s_nop 0
	v_cndmask_b32_e32 v7, v202, v7, vcc
	v_cmp_le_i32_e32 vcc, v181, v30
	v_subrev_u32_e32 v181, 52, v0
	v_max3_f32 v180, v180, v6, v7
	v_cndmask_b32_e32 v8, v202, v8, vcc
	v_cmp_le_i32_e32 vcc, v181, v30
	v_subrev_u32_e32 v181, 47, v0
	s_nop 0
	v_cndmask_b32_e32 v9, v202, v9, vcc
	v_cmp_le_i32_e32 vcc, v181, v30
	v_subrev_u32_e32 v181, 46, v0
	v_max3_f32 v180, v180, v8, v9
	v_cndmask_b32_e32 v10, v202, v10, vcc
	v_cmp_le_i32_e32 vcc, v181, v30
	v_subrev_u32_e32 v181, 45, v0
	s_nop 0
	v_cndmask_b32_e32 v11, v202, v11, vcc
	v_cmp_le_i32_e32 vcc, v181, v30
	v_subrev_u32_e32 v181, 44, v0
	v_max3_f32 v180, v180, v10, v11
	v_cndmask_b32_e32 v12, v202, v12, vcc
	v_cmp_le_i32_e32 vcc, v181, v30
	v_subrev_u32_e32 v181, 39, v0
	s_nop 0
	v_cndmask_b32_e32 v13, v202, v13, vcc
	v_cmp_le_i32_e32 vcc, v181, v30
	v_subrev_u32_e32 v181, 38, v0
	v_max3_f32 v180, v180, v12, v13
	v_cndmask_b32_e32 v14, v202, v14, vcc
	v_cmp_le_i32_e32 vcc, v181, v30
	v_subrev_u32_e32 v181, 37, v0
	v_subrev_u32_e32 v0, 36, v0
	v_cndmask_b32_e32 v15, v202, v15, vcc
	v_cmp_le_i32_e32 vcc, v181, v30
	v_max3_f32 v180, v180, v14, v15
	s_nop 0
	v_cndmask_b32_e32 v16, v202, v16, vcc
	v_cmp_le_i32_e32 vcc, v0, v30
	s_nop 1
	v_cndmask_b32_e32 v17, v202, v17, vcc
	v_max3_f32 v0, v180, v16, v17
